# attention: first Q.K half-step opens with its first MFMA instead of 7 VALU ops
# baseline (speedup 1.0000x reference)
; #define WAIT_BAR(N) asm volatile("s_waitcnt vmcnt(" #N ") lgkmcnt(0)\n\ts_barrier":::"memory")
;   #define RESC() do{}while(0)
;   #define ROT() do{sl_prev=sl_cur;sl_cur=sl_next;sl_next=(sl_next==(NSLOT-1)*SLOTB)?0:sl_next+SLOTB;}while(0)
; template<int THRL> __device__ __forceinline__ void attn_unit(int b,int h,int qb,const bf16*Q,const bf16*__restrict__ K,const bf16*__restrict__ V,bf16*O,char*shm,float m2){
;     ...
;   int t=1;
;   for(;t+5<NT;t+=2){
;     STEP(pB0,pB1,pA0,pA1,t,true,true,true);     WAIT_BAR(2); RESC(); ROT();
.LBB0_829:
	v_add_u32_e32 v190, s17, v220
	ds_read_b64_tr_b16 v[230:231], v190 offset:24576
	ds_read_b64_tr_b16 v[232:233], v190 offset:25088
	s_waitcnt lgkmcnt(9)
	v_mfma_f32_32x32x16_bf16 v[114:129], v[98:101], v[174:177], v[50:65]
	v_exp_f32_e32 v78, v78
	v_add_f32_e32 v102, v82, v83
	v_add_f32_e32 v102, v84, v102
	v_add_f32_e32 v102, v85, v102
	v_add_f32_e32 v102, v86, v102
	v_add_f32_e32 v102, v87, v102
	v_cvt_pk_bf16_f32 v166, v82, v83
	v_cvt_pk_bf16_f32 v167, v84, v85
	ds_read_b64_tr_b16 v[82:83], v190 offset:28672
	ds_read_b64_tr_b16 v[84:85], v190 offset:29184
	v_add_f32_e32 v98, v88, v102
	v_add_f32_e32 v98, v89, v98
	v_add_f32_e32 v98, v90, v98
	v_add_f32_e32 v146, v91, v98
	s_waitcnt lgkmcnt(10)
	v_mfma_f32_32x32x16_bf16 v[98:113], v[182:185], v[174:177], v[50:65]
	v_exp_f32_e32 v79, v79
	v_cvt_pk_bf16_f32 v168, v86, v87
	v_cvt_pk_bf16_f32 v169, v88, v89
	ds_read_b64_tr_b16 v[86:87], v190 offset:25600
	ds_read_b64_tr_b16 v[88:89], v190 offset:26112
	v_add_f32_e32 v146, v92, v146
	v_add_f32_e32 v146, v93, v146
	v_add_f32_e32 v146, v94, v146
	v_add_f32_e32 v146, v95, v146
	v_cvt_pk_bf16_f32 v158, v90, v91
	v_cvt_pk_bf16_f32 v159, v92, v93
	s_waitcnt lgkmcnt(11)
	v_mfma_f32_32x32x16_bf16 v[114:129], v[186:189], v[170:173], v[114:129]
	v_exp_f32_e32 v80, v80
	ds_read_b64_tr_b16 v[90:91], v190 offset:29696
	ds_read_b64_tr_b16 v[92:93], v190 offset:30208
	s_waitcnt lgkmcnt(12)
	v_mfma_f32_32x32x16_bf16 v[98:113], v[178:181], v[170:173], v[98:113]
	v_exp_f32_e32 v81, v81
	v_add_f32_e32 v146, v96, v146
	v_add_f32_e32 v146, v97, v146
	v_add_f32_e32 v146, v66, v146
	v_add_f32_e32 v146, v67, v146
	v_cvt_pk_bf16_f32 v160, v94, v95
	v_cvt_pk_bf16_f32 v161, v96, v97
	ds_read_b64_tr_b16 v[94:95], v190 offset:26624
	ds_read_b64_tr_b16 v[96:97], v190 offset:27136
	s_waitcnt lgkmcnt(13)
	v_mfma_f32_32x32x16_bf16 v[114:129], v[142:145], v[162:165], v[114:129]
	v_add_f32_e32 v142, v68, v146
	v_add_f32_e32 v142, v69, v142
	v_add_f32_e32 v142, v70, v142
	v_add_f32_e32 v142, v71, v142
	v_cvt_pk_bf16_f32 v150, v66, v67
	v_cvt_pk_bf16_f32 v151, v68, v69
	ds_read_b64_tr_b16 v[66:67], v190 offset:30720
	ds_read_b64_tr_b16 v[68:69], v190 offset:31232
	s_waitcnt lgkmcnt(14)
	v_mfma_f32_32x32x16_bf16 v[98:113], v[138:141], v[162:165], v[98:113]
	v_add_f32_e32 v138, v72, v142
	v_add_f32_e32 v138, v73, v138
	v_add_f32_e32 v138, v74, v138
	v_add_f32_e32 v138, v75, v138
	v_cvt_pk_bf16_f32 v152, v70, v71
	v_cvt_pk_bf16_f32 v153, v72, v73
	ds_read_b64_tr_b16 v[70:71], v190 offset:27648
	ds_read_b64_tr_b16 v[72:73], v190 offset:28160
	s_waitcnt lgkmcnt(14)
	v_mfma_f32_32x32x16_bf16 v[114:129], v[134:137], v[154:157], v[114:129]
	v_add_f32_e32 v134, v76, v138
	v_add_f32_e32 v134, v77, v134
	v_add_f32_e32 v134, v78, v134
	v_add_f32_e32 v134, v79, v134
	v_cvt_pk_bf16_f32 v146, v74, v75
	v_cvt_pk_bf16_f32 v147, v76, v77
	ds_read_b64_tr_b16 v[74:75], v190 offset:31744
	ds_read_b64_tr_b16 v[76:77], v190 offset:32256
	v_mfma_f32_32x32x16_bf16 v[98:113], v[130:133], v[154:157], v[98:113]
	v_add_f32_e32 v130, v80, v134
	v_add_f32_e32 v130, v81, v130
	v_add_f32_e32 v130, 0, v130
	v_cvt_pk_bf16_f32 v148, v78, v79
	v_cvt_pk_bf16_f32 v149, v80, v81
	v_lshl_add_u64 v[78:79], v[214:215], 0, s[48:49]
	s_add_i32 s0, s16, s12
	s_mov_b32 s17, m0
	s_mov_b32 m0, s0
	s_nop 0
	global_load_lds_dwordx4 v[78:79], off
	s_mov_b32 m0, s17
	v_lshl_add_u64 v[78:79], v[216:217], 0, s[42:43]
	s_add_i32 s0, s15, s4
	s_mov_b32 s17, m0
	s_mov_b32 m0, s0
	s_nop 0
	global_load_lds_dwordx4 v[78:79], off
	s_mov_b32 m0, s17
	v_add_f32_e32 v190, v199, v130
	s_waitcnt lgkmcnt(14)
	v_mfma_f32_32x32x16_bf16 v[18:33], v[166:169], v[230:233], v[18:33]
	v_exp_f32_e32 v114, v114
	v_exp_f32_e32 v115, v115
	v_exp_f32_e32 v116, v116
	v_exp_f32_e32 v117, v117
	s_waitcnt lgkmcnt(12)
	v_mfma_f32_32x32x16_bf16 v[34:49], v[166:169], v[82:85], v[34:49]
	v_exp_f32_e32 v118, v118
	v_exp_f32_e32 v119, v119
	v_exp_f32_e32 v120, v120
	v_exp_f32_e32 v121, v121
	v_add_u32_e32 v82, s15, v219
	ds_read_b128 v[78:81], v82
	ds_read_b128 v[134:137], v82 offset:512
	s_waitcnt lgkmcnt(12)
	v_mfma_f32_32x32x16_bf16 v[18:33], v[158:161], v[86:89], v[18:33]
	v_exp_f32_e32 v122, v122
	v_exp_f32_e32 v123, v123
	v_exp_f32_e32 v124, v124
	v_exp_f32_e32 v125, v125
	ds_read_b128 v[138:141], v82 offset:2048
	ds_read_b128 v[142:145], v82 offset:2560
	s_waitcnt lgkmcnt(12)
	v_mfma_f32_32x32x16_bf16 v[34:49], v[158:161], v[90:93], v[34:49]
	v_exp_f32_e32 v126, v126
	v_exp_f32_e32 v127, v127
	v_exp_f32_e32 v128, v128
	v_exp_f32_e32 v129, v129
	ds_read_b128 v[178:181], v82 offset:4096
	ds_read_b128 v[182:185], v82 offset:4608
	s_waitcnt lgkmcnt(12)
	v_mfma_f32_32x32x16_bf16 v[18:33], v[150:153], v[94:97], v[18:33]
	v_exp_f32_e32 v98, v98
	v_exp_f32_e32 v99, v99
	v_exp_f32_e32 v100, v100
	v_exp_f32_e32 v101, v101
	ds_read_b128 v[186:189], v82 offset:6144
	ds_read_b128 v[130:133], v82 offset:6656
	s_waitcnt lgkmcnt(12)
	v_mfma_f32_32x32x16_bf16 v[34:49], v[150:153], v[66:69], v[34:49]
	v_exp_f32_e32 v102, v102
	v_exp_f32_e32 v103, v103
	v_exp_f32_e32 v104, v104
	v_exp_f32_e32 v105, v105
	s_waitcnt lgkmcnt(10)
	v_mfma_f32_32x32x16_bf16 v[18:33], v[146:149], v[70:73], v[18:33]
	v_exp_f32_e32 v106, v106
	v_exp_f32_e32 v107, v107
	v_exp_f32_e32 v108, v108
	v_exp_f32_e32 v109, v109
	s_waitcnt lgkmcnt(8)
	v_mfma_f32_32x32x16_bf16 v[34:49], v[146:149], v[74:77], v[34:49]
	s_waitcnt vmcnt(2) lgkmcnt(0)
	s_barrier
; #define WAIT_BAR(N) asm volatile("s_waitcnt vmcnt(" #N ") lgkmcnt(0)\n\ts_barrier":::"memory")
;   #define RESC() do{}while(0)
;   #define ROT() do{sl_prev=sl_cur;sl_cur=sl_next;sl_next=(sl_next==(NSLOT-1)*SLOTB)?0:sl_next+SLOTB;}while(0)
; template<int THRL> __device__ __forceinline__ void attn_unit(int b,int h,int qb,const bf16*Q,const bf16*__restrict__ K,const bf16*__restrict__ V,bf16*O,char*shm,float m2){
;     ...
;   int t=1;
;   for(;t+5<NT;t+=2){
;     STEP(pB0,pB1,pA0,pA1,t,true,true,true);     WAIT_BAR(2); RESC(); ROT();
;     STEP(pA0,pA1,pB0,pB1,t+1,true,true,true);   WAIT_BAR(2); RESC(); ROT();
	s_add_i32 s0, s15, 0x2000
	s_cmpk_lg_i32 s15, 0x4000
	s_cselect_b32 s0, s0, 0
	v_add_u32_e32 v199, s16, v220
	ds_read_b64_tr_b16 v[230:231], v199 offset:24576
	ds_read_b64_tr_b16 v[232:233], v199 offset:25088
	s_waitcnt lgkmcnt(9)
	v_mfma_f32_32x32x16_bf16 v[82:97], v[78:81], v[174:177], v[50:65]
	v_exp_f32_e32 v110, v110
	v_add_f32_e32 v66, v114, v115
	v_add_f32_e32 v66, v116, v66
	v_add_f32_e32 v66, v117, v66
	v_add_f32_e32 v66, v118, v66
	v_add_f32_e32 v66, v119, v66
	v_cvt_pk_bf16_f32 v166, v114, v115
	v_cvt_pk_bf16_f32 v167, v116, v117
	ds_read_b64_tr_b16 v[114:115], v199 offset:28672
	ds_read_b64_tr_b16 v[116:117], v199 offset:29184
	v_add_f32_e32 v66, v120, v66
	v_add_f32_e32 v66, v121, v66
	v_add_f32_e32 v66, v122, v66
	v_add_f32_e32 v146, v123, v66
	s_waitcnt lgkmcnt(10)
	v_mfma_f32_32x32x16_bf16 v[66:81], v[134:137], v[174:177], v[50:65]
	v_exp_f32_e32 v111, v111
	v_cvt_pk_bf16_f32 v168, v118, v119
	v_cvt_pk_bf16_f32 v169, v120, v121
	ds_read_b64_tr_b16 v[118:119], v199 offset:25600
	ds_read_b64_tr_b16 v[120:121], v199 offset:26112
	s_waitcnt lgkmcnt(11)
	v_mfma_f32_32x32x16_bf16 v[82:97], v[138:141], v[170:173], v[82:97]
	v_exp_f32_e32 v112, v112
	v_add_f32_e32 v134, v124, v146
	v_add_f32_e32 v134, v125, v134
	v_add_f32_e32 v134, v126, v134
	v_add_f32_e32 v134, v127, v134
	v_cvt_pk_bf16_f32 v158, v122, v123
	v_cvt_pk_bf16_f32 v159, v124, v125
	ds_read_b64_tr_b16 v[122:123], v199 offset:29696
	ds_read_b64_tr_b16 v[124:125], v199 offset:30208
	s_waitcnt lgkmcnt(12)
	v_mfma_f32_32x32x16_bf16 v[66:81], v[142:145], v[170:173], v[66:81]
	v_exp_f32_e32 v113, v113
	v_add_f32_e32 v134, v128, v134
	v_add_f32_e32 v134, v129, v134
	v_add_f32_e32 v134, v98, v134
	v_add_f32_e32 v134, v99, v134
	v_cvt_pk_bf16_f32 v160, v126, v127
	v_cvt_pk_bf16_f32 v161, v128, v129
	ds_read_b64_tr_b16 v[126:127], v199 offset:26624
	ds_read_b64_tr_b16 v[128:129], v199 offset:27136
	s_waitcnt lgkmcnt(13)
	v_mfma_f32_32x32x16_bf16 v[82:97], v[178:181], v[162:165], v[82:97]
	v_add_f32_e32 v134, v100, v134
	v_add_f32_e32 v134, v101, v134
	v_add_f32_e32 v134, v102, v134
	v_add_f32_e32 v134, v103, v134
	v_cvt_pk_bf16_f32 v150, v98, v99
	v_cvt_pk_bf16_f32 v151, v100, v101
	ds_read_b64_tr_b16 v[234:235], v199 offset:30720
	ds_read_b64_tr_b16 v[236:237], v199 offset:31232
	s_waitcnt lgkmcnt(14)
	v_mfma_f32_32x32x16_bf16 v[66:81], v[182:185], v[162:165], v[66:81]
	v_add_f32_e32 v98, v104, v134
	v_add_f32_e32 v98, v105, v98
	v_add_f32_e32 v98, v106, v98
	v_add_f32_e32 v98, v107, v98
	v_cvt_pk_bf16_f32 v152, v102, v103
	v_cvt_pk_bf16_f32 v153, v104, v105
	ds_read_b64_tr_b16 v[102:103], v199 offset:27648
	ds_read_b64_tr_b16 v[104:105], v199 offset:28160
	s_waitcnt lgkmcnt(14)
	v_mfma_f32_32x32x16_bf16 v[82:97], v[186:189], v[154:157], v[82:97]
	v_add_f32_e32 v98, v108, v98
	v_add_f32_e32 v98, v109, v98
	v_add_f32_e32 v98, v110, v98
	v_add_f32_e32 v98, v111, v98
	v_cvt_pk_bf16_f32 v146, v106, v107
	v_cvt_pk_bf16_f32 v147, v108, v109
	ds_read_b64_tr_b16 v[106:107], v199 offset:31744
	ds_read_b64_tr_b16 v[108:109], v199 offset:32256
	v_mfma_f32_32x32x16_bf16 v[66:81], v[130:133], v[154:157], v[66:81]
	v_add_f32_e32 v98, v112, v98
	v_add_f32_e32 v98, v113, v98
	v_add_f32_e32 v98, 0, v98
	v_cvt_pk_bf16_f32 v148, v110, v111
	v_cvt_pk_bf16_f32 v149, v112, v113
	s_mov_b64 s[16:17], 0x10000
	v_add_f32_e32 v199, v190, v98
	v_lshl_add_u64 v[98:99], v[214:215], 0, s[16:17]
	s_add_i32 s16, s15, s12
	s_mov_b32 s17, m0
	s_mov_b32 m0, s16
	s_nop 0
	global_load_lds_dwordx4 v[98:99], off
	s_mov_b32 m0, s17
	v_lshl_add_u64 v[216:217], v[216:217], 0, s[46:47]
	s_add_i32 s16, s0, s4
	s_mov_b32 s17, m0
	s_mov_b32 m0, s16
	s_nop 0
	global_load_lds_dwordx4 v[216:217], off
	s_mov_b32 m0, s17
	s_waitcnt lgkmcnt(14)
	v_mfma_f32_32x32x16_bf16 v[18:33], v[166:169], v[230:233], v[18:33]
	v_exp_f32_e32 v82, v82
	v_exp_f32_e32 v83, v83
	v_exp_f32_e32 v84, v84
	v_exp_f32_e32 v85, v85
	s_waitcnt lgkmcnt(12)
	v_mfma_f32_32x32x16_bf16 v[34:49], v[166:169], v[114:117], v[34:49]
	v_exp_f32_e32 v86, v86
	v_exp_f32_e32 v87, v87
	v_exp_f32_e32 v88, v88
	v_exp_f32_e32 v89, v89
	v_add_u32_e32 v110, s0, v219
	ds_read_b128 v[98:101], v110
	ds_read_b128 v[182:185], v110 offset:512
	s_waitcnt lgkmcnt(12)
	v_mfma_f32_32x32x16_bf16 v[18:33], v[158:161], v[118:121], v[18:33]
	v_exp_f32_e32 v90, v90
	v_exp_f32_e32 v91, v91
	v_exp_f32_e32 v92, v92
	v_exp_f32_e32 v93, v93
	ds_read_b128 v[186:189], v110 offset:2048
	ds_read_b128 v[178:181], v110 offset:2560
	s_waitcnt lgkmcnt(12)
	v_mfma_f32_32x32x16_bf16 v[34:49], v[158:161], v[122:125], v[34:49]
	v_exp_f32_e32 v94, v94
	v_exp_f32_e32 v95, v95
	v_exp_f32_e32 v96, v96
	v_exp_f32_e32 v97, v97
	ds_read_b128 v[142:145], v110 offset:4096
	ds_read_b128 v[138:141], v110 offset:4608
	s_waitcnt lgkmcnt(12)
	v_mfma_f32_32x32x16_bf16 v[18:33], v[150:153], v[126:129], v[18:33]
	v_exp_f32_e32 v66, v66
	v_exp_f32_e32 v67, v67
	v_exp_f32_e32 v68, v68
	v_exp_f32_e32 v69, v69
	ds_read_b128 v[134:137], v110 offset:6144
	ds_read_b128 v[130:133], v110 offset:6656
	s_waitcnt lgkmcnt(12)
	v_mfma_f32_32x32x16_bf16 v[34:49], v[150:153], v[234:237], v[34:49]
	v_exp_f32_e32 v70, v70
	v_exp_f32_e32 v71, v71
	v_exp_f32_e32 v72, v72
	v_exp_f32_e32 v73, v73
	s_waitcnt lgkmcnt(10)
	v_mfma_f32_32x32x16_bf16 v[18:33], v[146:149], v[102:105], v[18:33]
	v_exp_f32_e32 v74, v74
	v_exp_f32_e32 v75, v75
	v_exp_f32_e32 v76, v76
	v_exp_f32_e32 v77, v77
	s_waitcnt lgkmcnt(8)
	v_mfma_f32_32x32x16_bf16 v[34:49], v[146:149], v[106:109], v[34:49]
	s_add_i32 s18, s0, 0x2000
	s_waitcnt vmcnt(2) lgkmcnt(0)
	s_barrier
; #define WAIT_BAR(N) asm volatile("s_waitcnt vmcnt(" #N ") lgkmcnt(0)\n\ts_barrier":::"memory")
;   #define RESC() do{}while(0)
;   #define ROT() do{sl_prev=sl_cur;sl_cur=sl_next;sl_next=(sl_next==(NSLOT-1)*SLOTB)?0:sl_next+SLOTB;}while(0)
;   #define ENDW(tt) do{ if((tt)+3<NT){WAIT_BAR(2);} else if((tt)+2<NT){WAIT_BAR(1);} else {WAIT_BAR(0);} }while(0)
; template<int THRL> __device__ __forceinline__ void attn_unit(int b,int h,int qb,const bf16*Q,const bf16*__restrict__ K,const bf16*__restrict__ V,bf16*O,char*shm,float m2){
;     ...
;   int t=1;
;   for(;t+5<NT;t+=2){
;     STEP(pB0,pB1,pA0,pA1,t,true,true,true);     WAIT_BAR(2); RESC(); ROT();
;     STEP(pA0,pA1,pB0,pB1,t+1,true,true,true);   WAIT_BAR(2); RESC(); ROT();
;   }
;     ...
;   for(;t+1<NT;t+=2){
;     STEP(pB0,pB1,pA0,pA1,t,(t+3<NT),(t+1<NT),(t+1<NT));       ENDW(t);   RESC(); ROT();
	s_cmpk_lg_i32 s0, 0x4000
	s_mov_b32 s17, s15
	s_cselect_b32 s15, s18, 0
	s_add_i32 s14, s14, 2
	v_lshl_add_u64 v[214:215], v[214:215], 0, s[46:47]
	s_mov_b32 s16, s0
	s_cmpk_gt_u32 s14, 0x78
	s_cbranch_scc0 .LBB0_829
	v_exp_f32_e32 v78, v78
	v_exp_f32_e32 v79, v79
	v_exp_f32_e32 v80, v80
	v_exp_f32_e32 v81, v81
	s_and_b32 s0, s13, 0x3fffffc0
	s_lshl_b32 s0, s0, 2
	s_add_i32 s0, s0, 0
	ds_read_b64_tr_b16 v[214:215], v220 offset:40960
	ds_read_b64_tr_b16 v[216:217], v220 offset:41472
	v_add_f32_e32 v102, v82, v83
	v_add_f32_e32 v102, v84, v102
	v_add_f32_e32 v102, v85, v102
	v_add_f32_e32 v102, v86, v102
	v_add_f32_e32 v102, v87, v102
	v_cvt_pk_bf16_f32 v166, v82, v83
	v_cvt_pk_bf16_f32 v167, v84, v85
	s_waitcnt lgkmcnt(9)
	v_mfma_f32_32x32x16_bf16 v[114:129], v[98:101], v[174:177], v[50:65]
	ds_read_b64_tr_b16 v[82:83], v220 offset:45056
	ds_read_b64_tr_b16 v[84:85], v220 offset:45568
	v_add_f32_e32 v98, v88, v102
	v_add_f32_e32 v98, v89, v98
	v_add_f32_e32 v98, v90, v98
	v_add_f32_e32 v146, v91, v98
	v_cvt_pk_bf16_f32 v168, v86, v87
	v_cvt_pk_bf16_f32 v169, v88, v89
	s_waitcnt lgkmcnt(10)
	v_mfma_f32_32x32x16_bf16 v[98:113], v[182:185], v[174:177], v[50:65]
	ds_read_b64_tr_b16 v[86:87], v220 offset:41984
	ds_read_b64_tr_b16 v[88:89], v220 offset:42496
	v_add_f32_e32 v146, v92, v146
	v_add_f32_e32 v146, v93, v146
	v_add_f32_e32 v146, v94, v146
	v_add_f32_e32 v146, v95, v146
	v_cvt_pk_bf16_f32 v158, v90, v91
	v_cvt_pk_bf16_f32 v159, v92, v93
	s_waitcnt lgkmcnt(11)
	v_mfma_f32_32x32x16_bf16 v[114:129], v[186:189], v[170:173], v[114:129]
	ds_read_b64_tr_b16 v[90:91], v220 offset:46080
	ds_read_b64_tr_b16 v[92:93], v220 offset:46592
	v_add_f32_e32 v146, v96, v146
	v_add_f32_e32 v146, v97, v146
	v_add_f32_e32 v146, v66, v146
	v_add_f32_e32 v146, v67, v146
	v_cvt_pk_bf16_f32 v160, v94, v95
	v_cvt_pk_bf16_f32 v161, v96, v97
	s_waitcnt lgkmcnt(12)
	v_mfma_f32_32x32x16_bf16 v[98:113], v[178:181], v[170:173], v[98:113]
	ds_read_b64_tr_b16 v[94:95], v220 offset:43008
	ds_read_b64_tr_b16 v[96:97], v220 offset:43520
	s_waitcnt lgkmcnt(13)
	v_mfma_f32_32x32x16_bf16 v[114:129], v[142:145], v[162:165], v[114:129]
	v_add_f32_e32 v142, v68, v146
	v_add_f32_e32 v142, v69, v142
	v_add_f32_e32 v142, v70, v142
	v_add_f32_e32 v142, v71, v142
	v_cvt_pk_bf16_f32 v150, v66, v67
	v_cvt_pk_bf16_f32 v151, v68, v69
	ds_read_b64_tr_b16 v[66:67], v220 offset:47104
	ds_read_b64_tr_b16 v[68:69], v220 offset:47616
	s_waitcnt lgkmcnt(14)
	v_mfma_f32_32x32x16_bf16 v[98:113], v[138:141], v[162:165], v[98:113]
	v_add_f32_e32 v138, v72, v142
	v_add_f32_e32 v138, v73, v138
	v_add_f32_e32 v138, v74, v138
	v_add_f32_e32 v138, v75, v138
	v_cvt_pk_bf16_f32 v152, v70, v71
	v_cvt_pk_bf16_f32 v153, v72, v73
	ds_read_b64_tr_b16 v[70:71], v220 offset:44032
	ds_read_b64_tr_b16 v[72:73], v220 offset:44544
	s_waitcnt lgkmcnt(14)
	v_mfma_f32_32x32x16_bf16 v[114:129], v[134:137], v[154:157], v[114:129]
	v_add_f32_e32 v134, v76, v138
	v_add_f32_e32 v134, v77, v134
	v_add_f32_e32 v134, v78, v134
	v_add_f32_e32 v134, v79, v134
	v_cvt_pk_bf16_f32 v146, v74, v75
	v_cvt_pk_bf16_f32 v147, v76, v77
	ds_read_b64_tr_b16 v[74:75], v220 offset:48128
	ds_read_b64_tr_b16 v[76:77], v220 offset:48640
	v_mfma_f32_32x32x16_bf16 v[98:113], v[130:133], v[154:157], v[98:113]
	v_add_f32_e32 v130, v80, v134
	v_add_f32_e32 v130, v81, v130
	v_add_f32_e32 v130, 0, v130
	v_cvt_pk_bf16_f32 v148, v78, v79
	v_cvt_pk_bf16_f32 v149, v80, v81
	v_lshl_add_u64 v[78:79], v[212:213], 0, s[50:51]
	s_mov_b32 s13, m0
	s_mov_b32 m0, s12
	s_nop 0
	global_load_lds_dwordx4 v[78:79], off
	s_mov_b32 m0, s13
	s_mov_b64 s[12:13], 0x1f0000
	s_cmp_lg_u32 0, -1
	v_lshl_add_u64 v[78:79], v[210:211], 0, s[12:13]
	s_cselect_b32 s12, 0, 0
	s_add_i32 s12, s12, s5
	s_add_i32 s5, s12, 0x8000
	s_mov_b32 s13, m0
	s_mov_b32 m0, s5
	s_nop 0
	global_load_lds_dwordx4 v[78:79], off
	s_mov_b32 m0, s13
	v_add_f32_e32 v190, v199, v130
	s_waitcnt lgkmcnt(14)
	v_mfma_f32_32x32x16_bf16 v[18:33], v[166:169], v[214:217], v[18:33]
	v_exp_f32_e32 v114, v114
	v_exp_f32_e32 v115, v115
	v_exp_f32_e32 v116, v116
	v_exp_f32_e32 v117, v117
	s_waitcnt lgkmcnt(12)
	v_mfma_f32_32x32x16_bf16 v[34:49], v[166:169], v[82:85], v[34:49]
	v_exp_f32_e32 v118, v118
	v_exp_f32_e32 v119, v119
	v_exp_f32_e32 v120, v120
	v_exp_f32_e32 v121, v121
	ds_read_b128 v[78:81], v219 offset:8192
	ds_read_b128 v[178:181], v219 offset:8704
	s_waitcnt lgkmcnt(12)
	v_mfma_f32_32x32x16_bf16 v[18:33], v[158:161], v[86:89], v[18:33]
	v_exp_f32_e32 v122, v122
	v_exp_f32_e32 v123, v123
	v_exp_f32_e32 v124, v124
	v_exp_f32_e32 v125, v125
	ds_read_b128 v[86:89], v219 offset:10240
	ds_read_b128 v[182:185], v219 offset:10752
	s_waitcnt lgkmcnt(12)
	v_mfma_f32_32x32x16_bf16 v[34:49], v[158:161], v[90:93], v[34:49]
	v_exp_f32_e32 v126, v126
	v_exp_f32_e32 v127, v127
	v_exp_f32_e32 v128, v128
	v_exp_f32_e32 v129, v129
	ds_read_b128 v[90:93], v219 offset:12288
	ds_read_b128 v[186:189], v219 offset:12800
	s_waitcnt lgkmcnt(12)
	v_mfma_f32_32x32x16_bf16 v[18:33], v[150:153], v[94:97], v[18:33]
	v_exp_f32_e32 v98, v98
	v_exp_f32_e32 v99, v99
	v_exp_f32_e32 v100, v100
	v_exp_f32_e32 v101, v101
	ds_read_b128 v[94:97], v219 offset:14336
	ds_read_b128 v[82:85], v219 offset:14848
	s_waitcnt lgkmcnt(12)
	v_mfma_f32_32x32x16_bf16 v[34:49], v[150:153], v[66:69], v[34:49]
	v_exp_f32_e32 v102, v102
	v_exp_f32_e32 v103, v103
	v_exp_f32_e32 v104, v104
	v_exp_f32_e32 v105, v105
	s_waitcnt lgkmcnt(10)
	v_mfma_f32_32x32x16_bf16 v[18:33], v[146:149], v[70:73], v[18:33]
	v_exp_f32_e32 v106, v106
	v_exp_f32_e32 v107, v107
	v_exp_f32_e32 v108, v108
	v_exp_f32_e32 v109, v109
	s_waitcnt lgkmcnt(8)
	v_mfma_f32_32x32x16_bf16 v[34:49], v[146:149], v[74:77], v[34:49]
	v_exp_f32_e32 v110, v110
	v_exp_f32_e32 v111, v111
	v_exp_f32_e32 v112, v112
	v_exp_f32_e32 v113, v113
	s_waitcnt vmcnt(2) lgkmcnt(0)
	s_barrier
; #define WAIT_BAR(N) asm volatile("s_waitcnt vmcnt(" #N ") lgkmcnt(0)\n\ts_barrier":::"memory")
;   #define RESC() do{}while(0)
;   #define ROT() do{sl_prev=sl_cur;sl_cur=sl_next;sl_next=(sl_next==(NSLOT-1)*SLOTB)?0:sl_next+SLOTB;}while(0)
;   #define ENDW(tt) do{ if((tt)+3<NT){WAIT_BAR(2);} else if((tt)+2<NT){WAIT_BAR(1);} else {WAIT_BAR(0);} }while(0)
; template<int THRL> __device__ __forceinline__ void attn_unit(int b,int h,int qb,const bf16*Q,const bf16*__restrict__ K,const bf16*__restrict__ V,bf16*O,char*shm,float m2){
;     ...
;   int t=1;
;   for(;t+5<NT;t+=2){
;     STEP(pB0,pB1,pA0,pA1,t,true,true,true);     WAIT_BAR(2); RESC(); ROT();
;     STEP(pA0,pA1,pB0,pB1,t+1,true,true,true);   WAIT_BAR(2); RESC(); ROT();
;   }
;     ...
;   for(;t+1<NT;t+=2){
;     STEP(pB0,pB1,pA0,pA1,t,(t+3<NT),(t+1<NT),(t+1<NT));       ENDW(t);   RESC(); ROT();
;     STEP(pA0,pA1,pB0,pB1,t+1,(t+4<NT),(t+2<NT),(t+2<NT));     ENDW(t+1); RESC(); ROT();
	ds_read_b64_tr_b16 v[214:215], v220 offset:24576
	ds_read_b64_tr_b16 v[216:217], v220 offset:25088
	v_add_f32_e32 v66, v114, v115
	v_add_f32_e32 v66, v116, v66
	v_add_f32_e32 v66, v117, v66
	v_add_f32_e32 v66, v118, v66
	v_add_f32_e32 v66, v119, v66
	v_cvt_pk_bf16_f32 v166, v114, v115
	v_cvt_pk_bf16_f32 v167, v116, v117
	s_waitcnt lgkmcnt(9)
	v_mfma_f32_32x32x16_bf16 v[130:145], v[78:81], v[174:177], v[50:65]
	ds_read_b64_tr_b16 v[114:115], v220 offset:28672
	ds_read_b64_tr_b16 v[116:117], v220 offset:29184
	v_add_f32_e32 v66, v120, v66
	v_add_f32_e32 v66, v121, v66
	v_add_f32_e32 v66, v122, v66
	v_add_f32_e32 v146, v123, v66
	s_waitcnt lgkmcnt(10)
	v_mfma_f32_32x32x16_bf16 v[66:81], v[178:181], v[174:177], v[50:65]
	v_cvt_pk_bf16_f32 v168, v118, v119
	v_cvt_pk_bf16_f32 v169, v120, v121
	ds_read_b64_tr_b16 v[118:119], v220 offset:25600
	ds_read_b64_tr_b16 v[120:121], v220 offset:26112
	s_waitcnt lgkmcnt(11)
	v_mfma_f32_32x32x16_bf16 v[130:145], v[86:89], v[170:173], v[130:145]
	v_add_f32_e32 v86, v124, v146
	v_add_f32_e32 v86, v125, v86
	v_add_f32_e32 v86, v126, v86
	v_add_f32_e32 v146, v127, v86
	v_cvt_pk_bf16_f32 v158, v122, v123
	v_cvt_pk_bf16_f32 v159, v124, v125
	ds_read_b64_tr_b16 v[86:87], v220 offset:29696
	ds_read_b64_tr_b16 v[88:89], v220 offset:30208
	s_waitcnt lgkmcnt(12)
	v_mfma_f32_32x32x16_bf16 v[66:81], v[182:185], v[170:173], v[66:81]
	v_add_f32_e32 v122, v128, v146
	v_add_f32_e32 v122, v129, v122
	v_add_f32_e32 v122, v98, v122
	v_add_f32_e32 v146, v99, v122
	v_cvt_pk_bf16_f32 v160, v126, v127
	v_cvt_pk_bf16_f32 v161, v128, v129
	ds_read_b64_tr_b16 v[122:123], v220 offset:26624
	ds_read_b64_tr_b16 v[124:125], v220 offset:27136
	s_waitcnt lgkmcnt(13)
	v_mfma_f32_32x32x16_bf16 v[130:145], v[90:93], v[162:165], v[130:145]
	v_add_f32_e32 v90, v100, v146
	v_add_f32_e32 v90, v101, v90
	v_add_f32_e32 v90, v102, v90
	v_add_f32_e32 v126, v103, v90
	v_cvt_pk_bf16_f32 v150, v98, v99
	v_cvt_pk_bf16_f32 v151, v100, v101
	ds_read_b64_tr_b16 v[90:91], v220 offset:30720
	ds_read_b64_tr_b16 v[92:93], v220 offset:31232
	s_waitcnt lgkmcnt(14)
	v_mfma_f32_32x32x16_bf16 v[66:81], v[186:189], v[162:165], v[66:81]
	v_add_f32_e32 v98, v104, v126
	v_add_f32_e32 v98, v105, v98
	v_add_f32_e32 v98, v106, v98
	v_add_f32_e32 v98, v107, v98
	v_cvt_pk_bf16_f32 v152, v102, v103
	v_cvt_pk_bf16_f32 v153, v104, v105
	ds_read_b64_tr_b16 v[102:103], v220 offset:27648
	ds_read_b64_tr_b16 v[104:105], v220 offset:28160
	s_waitcnt lgkmcnt(14)
	v_mfma_f32_32x32x16_bf16 v[130:145], v[94:97], v[154:157], v[130:145]
	v_add_f32_e32 v94, v108, v98
	v_add_f32_e32 v94, v109, v94
	v_add_f32_e32 v94, v110, v94
	v_add_f32_e32 v98, v111, v94
	v_cvt_pk_bf16_f32 v146, v106, v107
	v_cvt_pk_bf16_f32 v147, v108, v109
	ds_read_b64_tr_b16 v[94:95], v220 offset:31744
	ds_read_b64_tr_b16 v[96:97], v220 offset:32256
	v_mfma_f32_32x32x16_bf16 v[66:81], v[82:85], v[154:157], v[66:81]
	v_add_f32_e32 v82, v112, v98
	v_add_f32_e32 v82, v113, v82
	v_add_f32_e32 v82, 0, v82
	v_cvt_pk_bf16_f32 v148, v110, v111
	v_cvt_pk_bf16_f32 v149, v112, v113
	s_nop 0
	v_add_f32_e32 v190, v190, v82
	v_lshl_add_u64 v[82:83], v[212:213], 0, s[52:53]
	s_add_i32 s13, s12, 0x2000
	s_mov_b32 s14, m0
	s_mov_b32 m0, s13
	s_nop 0
	global_load_lds_dwordx4 v[82:83], off
	s_mov_b32 m0, s14
	s_mov_b64 s[14:15], 0x1f4000
	v_lshl_add_u64 v[82:83], v[210:211], 0, s[14:15]
	s_add_i32 s12, s12, 0xa000
	s_mov_b32 s13, m0
	s_mov_b32 m0, s12
	s_nop 0
	global_load_lds_dwordx4 v[82:83], off
	s_mov_b32 m0, s13
	s_waitcnt lgkmcnt(14)
	v_mfma_f32_32x32x16_bf16 v[18:33], v[166:169], v[214:217], v[18:33]
	v_exp_f32_e32 v130, v130
	v_exp_f32_e32 v131, v131
	v_exp_f32_e32 v132, v132
	v_exp_f32_e32 v133, v133
	s_waitcnt lgkmcnt(12)
	v_mfma_f32_32x32x16_bf16 v[34:49], v[166:169], v[114:117], v[34:49]
	v_exp_f32_e32 v134, v134
	v_exp_f32_e32 v135, v135
	v_exp_f32_e32 v136, v136
	v_exp_f32_e32 v137, v137
	ds_read_b128 v[82:85], v219 offset:16384
	ds_read_b128 v[106:109], v219 offset:16896
	s_waitcnt lgkmcnt(12)
	v_mfma_f32_32x32x16_bf16 v[18:33], v[158:161], v[118:121], v[18:33]
	v_exp_f32_e32 v138, v138
	v_exp_f32_e32 v139, v139
	v_exp_f32_e32 v140, v140
	v_exp_f32_e32 v141, v141
	ds_read_b128 v[110:113], v219 offset:18432
	ds_read_b128 v[178:181], v219 offset:18944
	s_waitcnt lgkmcnt(12)
	v_mfma_f32_32x32x16_bf16 v[34:49], v[158:161], v[86:89], v[34:49]
	v_exp_f32_e32 v142, v142
	v_exp_f32_e32 v143, v143
	v_exp_f32_e32 v144, v144
	v_exp_f32_e32 v145, v145
	ds_read_b128 v[182:185], v219 offset:20480
	ds_read_b128 v[186:189], v219 offset:20992
	s_waitcnt lgkmcnt(12)
	v_mfma_f32_32x32x16_bf16 v[18:33], v[150:153], v[122:125], v[18:33]
	v_exp_f32_e32 v66, v66
	v_exp_f32_e32 v67, v67
	v_exp_f32_e32 v68, v68
	v_exp_f32_e32 v69, v69
	ds_read_b128 v[212:215], v219 offset:22528
	ds_read_b128 v[98:101], v219 offset:23040
	s_waitcnt lgkmcnt(12)
	v_mfma_f32_32x32x16_bf16 v[34:49], v[150:153], v[90:93], v[34:49]
	v_exp_f32_e32 v70, v70
	v_exp_f32_e32 v71, v71
	v_exp_f32_e32 v72, v72
	v_exp_f32_e32 v73, v73
	s_waitcnt lgkmcnt(10)
	v_mfma_f32_32x32x16_bf16 v[18:33], v[146:149], v[102:105], v[18:33]
	v_exp_f32_e32 v74, v74
	v_exp_f32_e32 v75, v75
	v_exp_f32_e32 v76, v76
	v_exp_f32_e32 v77, v77
	s_waitcnt lgkmcnt(8)
	v_mfma_f32_32x32x16_bf16 v[34:49], v[146:149], v[94:97], v[34:49]
	v_exp_f32_e32 v78, v78
	v_exp_f32_e32 v79, v79
	v_exp_f32_e32 v80, v80
	v_exp_f32_e32 v81, v81
	s_waitcnt vmcnt(2) lgkmcnt(0)
	s_barrier
; #define WAIT_BAR(N) asm volatile("s_waitcnt vmcnt(" #N ") lgkmcnt(0)\n\ts_barrier":::"memory")
;   #define RESC() do{}while(0)
;   #define ROT() do{sl_prev=sl_cur;sl_cur=sl_next;sl_next=(sl_next==(NSLOT-1)*SLOTB)?0:sl_next+SLOTB;}while(0)
;   #define ENDW(tt) do{ if((tt)+3<NT){WAIT_BAR(2);} else if((tt)+2<NT){WAIT_BAR(1);} else {WAIT_BAR(0);} }while(0)
; template<int THRL> __device__ __forceinline__ void attn_unit(int b,int h,int qb,const bf16*Q,const bf16*__restrict__ K,const bf16*__restrict__ V,bf16*O,char*shm,float m2){
;     ...
;   int t=1;
;   for(;t+5<NT;t+=2){
;     STEP(pB0,pB1,pA0,pA1,t,true,true,true);     WAIT_BAR(2); RESC(); ROT();
;     STEP(pA0,pA1,pB0,pB1,t+1,true,true,true);   WAIT_BAR(2); RESC(); ROT();
;   }
;     ...
;   for(;t+1<NT;t+=2){
;     STEP(pB0,pB1,pA0,pA1,t,(t+3<NT),(t+1<NT),(t+1<NT));       ENDW(t);   RESC(); ROT();
;     STEP(pA0,pA1,pB0,pB1,t+1,(t+4<NT),(t+2<NT),(t+2<NT));     ENDW(t+1); RESC(); ROT();
;   }
	ds_read_b64_tr_b16 v[102:103], v220 offset:32768
	ds_read_b64_tr_b16 v[104:105], v220 offset:33280
	v_add_f32_e32 v86, v130, v131
	v_add_f32_e32 v86, v132, v86
	v_add_f32_e32 v86, v133, v86
	v_add_f32_e32 v86, v134, v86
	v_add_f32_e32 v86, v135, v86
	v_cvt_pk_bf16_f32 v166, v130, v131
	v_cvt_pk_bf16_f32 v167, v132, v133
	s_waitcnt lgkmcnt(9)
	v_mfma_f32_32x32x16_bf16 v[114:129], v[82:85], v[174:177], v[50:65]
	ds_read_b64_tr_b16 v[130:131], v220 offset:36864
	ds_read_b64_tr_b16 v[132:133], v220 offset:37376
	v_add_f32_e32 v82, v136, v86
	v_add_f32_e32 v82, v137, v82
	v_add_f32_e32 v82, v138, v82
	v_add_f32_e32 v146, v139, v82
	v_cvt_pk_bf16_f32 v168, v134, v135
	v_cvt_pk_bf16_f32 v169, v136, v137
	s_waitcnt lgkmcnt(10)
	v_mfma_f32_32x32x16_bf16 v[82:97], v[106:109], v[174:177], v[50:65]
	ds_read_b64_tr_b16 v[106:107], v220 offset:33792
	ds_read_b64_tr_b16 v[108:109], v220 offset:34304
	s_waitcnt lgkmcnt(11)
	v_mfma_f32_32x32x16_bf16 v[114:129], v[110:113], v[170:173], v[114:129]
	v_add_f32_e32 v110, v140, v146
	v_add_f32_e32 v110, v141, v110
	v_add_f32_e32 v110, v142, v110
	v_add_f32_e32 v134, v143, v110
	v_cvt_pk_bf16_f32 v158, v138, v139
	v_cvt_pk_bf16_f32 v159, v140, v141
	ds_read_b64_tr_b16 v[110:111], v220 offset:37888
	ds_read_b64_tr_b16 v[112:113], v220 offset:38400
	v_add_f32_e32 v134, v144, v134
	v_add_f32_e32 v134, v145, v134
	v_add_f32_e32 v134, v66, v134
	v_add_f32_e32 v138, v67, v134
	v_cvt_pk_bf16_f32 v160, v142, v143
	v_cvt_pk_bf16_f32 v161, v144, v145
	s_waitcnt lgkmcnt(12)
	v_mfma_f32_32x32x16_bf16 v[82:97], v[178:181], v[170:173], v[82:97]
	ds_read_b64_tr_b16 v[134:135], v220 offset:34816
	ds_read_b64_tr_b16 v[136:137], v220 offset:35328
	v_add_f32_e32 v138, v68, v138
	v_add_f32_e32 v138, v69, v138
	v_add_f32_e32 v138, v70, v138
	v_add_f32_e32 v138, v71, v138
	v_cvt_pk_bf16_f32 v150, v66, v67
	v_cvt_pk_bf16_f32 v151, v68, v69
	s_waitcnt lgkmcnt(13)
	v_mfma_f32_32x32x16_bf16 v[114:129], v[182:185], v[162:165], v[114:129]
	ds_read_b64_tr_b16 v[66:67], v220 offset:38912
	ds_read_b64_tr_b16 v[68:69], v220 offset:39424
	v_add_f32_e32 v138, v72, v138
	v_add_f32_e32 v138, v73, v138
	v_add_f32_e32 v138, v74, v138
	v_add_f32_e32 v138, v75, v138
	v_cvt_pk_bf16_f32 v152, v70, v71
	v_cvt_pk_bf16_f32 v153, v72, v73
	s_waitcnt lgkmcnt(14)
	v_mfma_f32_32x32x16_bf16 v[82:97], v[186:189], v[162:165], v[82:97]
	ds_read_b64_tr_b16 v[70:71], v220 offset:35840
	ds_read_b64_tr_b16 v[72:73], v220 offset:36352
	v_add_f32_e32 v138, v76, v138
	v_add_f32_e32 v138, v77, v138
	v_add_f32_e32 v138, v78, v138
	v_add_f32_e32 v138, v79, v138
	v_cvt_pk_bf16_f32 v146, v74, v75
	v_cvt_pk_bf16_f32 v147, v76, v77
	s_waitcnt lgkmcnt(14)
	v_mfma_f32_32x32x16_bf16 v[114:129], v[212:215], v[154:157], v[114:129]
	ds_read_b64_tr_b16 v[74:75], v220 offset:39936
	ds_read_b64_tr_b16 v[76:77], v220 offset:40448
	v_mfma_f32_32x32x16_bf16 v[82:97], v[98:101], v[154:157], v[82:97]
	v_add_f32_e32 v98, v80, v138
	v_add_f32_e32 v98, v81, v98
	v_add_f32_e32 v98, 0, v98
	v_cvt_pk_bf16_f32 v148, v78, v79
	v_cvt_pk_bf16_f32 v149, v80, v81
	v_lshl_add_u64 v[78:79], v[210:211], 0, s[50:51]
	s_mov_b32 s12, m0
	s_mov_b32 m0, s4
	s_nop 0
	global_load_lds_dwordx4 v[78:79], off
	s_mov_b32 m0, s12
	v_add_f32_e32 v190, v190, v98
	s_waitcnt lgkmcnt(14)
	v_mfma_f32_32x32x16_bf16 v[18:33], v[166:169], v[102:105], v[18:33]
	v_exp_f32_e32 v114, v114
	v_exp_f32_e32 v115, v115
	v_exp_f32_e32 v116, v116
	v_exp_f32_e32 v117, v117
	s_waitcnt lgkmcnt(12)
	v_mfma_f32_32x32x16_bf16 v[34:49], v[166:169], v[130:133], v[34:49]
	v_exp_f32_e32 v118, v118
	v_exp_f32_e32 v119, v119
	v_exp_f32_e32 v120, v120
	v_exp_f32_e32 v121, v121
	ds_read_b128 v[78:81], v219
	ds_read_b128 v[138:141], v219 offset:512
	s_waitcnt lgkmcnt(12)
	v_mfma_f32_32x32x16_bf16 v[18:33], v[158:161], v[106:109], v[18:33]
	v_exp_f32_e32 v122, v122
	v_exp_f32_e32 v123, v123
	v_exp_f32_e32 v124, v124
	v_exp_f32_e32 v125, v125
	ds_read_b128 v[142:145], v219 offset:2048
	ds_read_b128 v[178:181], v219 offset:2560
	s_waitcnt lgkmcnt(12)
	v_mfma_f32_32x32x16_bf16 v[34:49], v[158:161], v[110:113], v[34:49]
	v_exp_f32_e32 v126, v126
	v_exp_f32_e32 v127, v127
	v_exp_f32_e32 v128, v128
	v_exp_f32_e32 v129, v129
	ds_read_b128 v[182:185], v219 offset:4096
	ds_read_b128 v[186:189], v219 offset:4608
	s_waitcnt lgkmcnt(12)
	v_mfma_f32_32x32x16_bf16 v[18:33], v[150:153], v[134:137], v[18:33]
	v_exp_f32_e32 v82, v82
	v_exp_f32_e32 v83, v83
	v_exp_f32_e32 v84, v84
	v_exp_f32_e32 v85, v85
	ds_read_b128 v[134:137], v219 offset:6144
	ds_read_b128 v[130:133], v219 offset:6656
	s_waitcnt lgkmcnt(12)
	v_mfma_f32_32x32x16_bf16 v[34:49], v[150:153], v[66:69], v[34:49]
	v_exp_f32_e32 v86, v86
	v_exp_f32_e32 v87, v87
	v_exp_f32_e32 v88, v88
	v_exp_f32_e32 v89, v89
	s_waitcnt lgkmcnt(10)
	v_mfma_f32_32x32x16_bf16 v[18:33], v[146:149], v[70:73], v[18:33]
	v_exp_f32_e32 v90, v90
	v_exp_f32_e32 v91, v91
	v_exp_f32_e32 v92, v92
	v_exp_f32_e32 v93, v93
	s_waitcnt lgkmcnt(8)
	v_mfma_f32_32x32x16_bf16 v[34:49], v[146:149], v[74:77], v[34:49]
	v_exp_f32_e32 v94, v94
	v_exp_f32_e32 v95, v95
	v_exp_f32_e32 v96, v96
	v_exp_f32_e32 v97, v97
	s_waitcnt vmcnt(1) lgkmcnt(0)
	s_barrier
; #define WAIT_BAR(N) asm volatile("s_waitcnt vmcnt(" #N ") lgkmcnt(0)\n\ts_barrier":::"memory")
;   #define RESC() do{}while(0)
;   #define ROT() do{sl_prev=sl_cur;sl_cur=sl_next;sl_next=(sl_next==(NSLOT-1)*SLOTB)?0:sl_next+SLOTB;}while(0)
;   #define ENDW(tt) do{ if((tt)+3<NT){WAIT_BAR(2);} else if((tt)+2<NT){WAIT_BAR(1);} else {WAIT_BAR(0);} }while(0)
; template<int THRL> __device__ __forceinline__ void attn_unit(int b,int h,int qb,const bf16*Q,const bf16*__restrict__ K,const bf16*__restrict__ V,bf16*O,char*shm,float m2){
;     ...
;   int t=1;
;   for(;t+5<NT;t+=2){
;     STEP(pB0,pB1,pA0,pA1,t,true,true,true);     WAIT_BAR(2); RESC(); ROT();
;     STEP(pA0,pA1,pB0,pB1,t+1,true,true,true);   WAIT_BAR(2); RESC(); ROT();
;   }
;     ...
;   for(;t+1<NT;t+=2){
;     STEP(pB0,pB1,pA0,pA1,t,(t+3<NT),(t+1<NT),(t+1<NT));       ENDW(t);   RESC(); ROT();
;     STEP(pA0,pA1,pB0,pB1,t+1,(t+4<NT),(t+2<NT),(t+2<NT));     ENDW(t+1); RESC(); ROT();
;   }
	ds_read_b64_tr_b16 v[212:213], v220 offset:40960
	ds_read_b64_tr_b16 v[214:215], v220 offset:41472
	v_add_f32_e32 v66, v114, v115
	v_add_f32_e32 v66, v116, v66
	v_add_f32_e32 v66, v117, v66
	v_add_f32_e32 v66, v118, v66
	v_add_f32_e32 v66, v119, v66
	v_cvt_pk_bf16_f32 v166, v114, v115
	v_cvt_pk_bf16_f32 v167, v116, v117
	s_waitcnt lgkmcnt(9)
	v_mfma_f32_32x32x16_bf16 v[98:113], v[78:81], v[174:177], v[50:65]
	ds_read_b64_tr_b16 v[114:115], v220 offset:45056
	ds_read_b64_tr_b16 v[116:117], v220 offset:45568
	v_add_f32_e32 v66, v120, v66
	v_add_f32_e32 v66, v121, v66
	v_add_f32_e32 v66, v122, v66
	v_add_f32_e32 v146, v123, v66
	s_waitcnt lgkmcnt(10)
	v_mfma_f32_32x32x16_bf16 v[66:81], v[138:141], v[174:177], v[50:65]
	v_cvt_pk_bf16_f32 v168, v118, v119
	v_cvt_pk_bf16_f32 v169, v120, v121
	ds_read_b64_tr_b16 v[138:139], v220 offset:41984
	ds_read_b64_tr_b16 v[140:141], v220 offset:42496
	v_add_f32_e32 v118, v124, v146
	v_add_f32_e32 v118, v125, v118
	v_add_f32_e32 v118, v126, v118
	v_add_f32_e32 v118, v127, v118
	v_cvt_pk_bf16_f32 v158, v122, v123
	v_cvt_pk_bf16_f32 v159, v124, v125
	s_waitcnt lgkmcnt(11)
	v_mfma_f32_32x32x16_bf16 v[98:113], v[142:145], v[170:173], v[98:113]
	ds_read_b64_tr_b16 v[120:121], v220 offset:46080
	ds_read_b64_tr_b16 v[122:123], v220 offset:46592
	s_waitcnt lgkmcnt(12)
	v_mfma_f32_32x32x16_bf16 v[66:81], v[178:181], v[170:173], v[66:81]
	v_add_f32_e32 v118, v128, v118
	v_add_f32_e32 v118, v129, v118
	v_add_f32_e32 v118, v82, v118
	v_add_f32_e32 v118, v83, v118
	v_cvt_pk_bf16_f32 v160, v126, v127
	v_cvt_pk_bf16_f32 v161, v128, v129
	ds_read_b64_tr_b16 v[124:125], v220 offset:43008
	ds_read_b64_tr_b16 v[126:127], v220 offset:43520
	v_add_f32_e32 v118, v84, v118
	v_add_f32_e32 v118, v85, v118
	v_add_f32_e32 v118, v86, v118
	v_add_f32_e32 v118, v87, v118
	v_cvt_pk_bf16_f32 v150, v82, v83
	v_cvt_pk_bf16_f32 v151, v84, v85
	s_waitcnt lgkmcnt(13)
	v_mfma_f32_32x32x16_bf16 v[98:113], v[182:185], v[162:165], v[98:113]
	ds_read_b64_tr_b16 v[82:83], v220 offset:47104
	ds_read_b64_tr_b16 v[84:85], v220 offset:47616
	s_waitcnt lgkmcnt(14)
	v_mfma_f32_32x32x16_bf16 v[66:81], v[186:189], v[162:165], v[66:81]
	v_add_f32_e32 v118, v88, v118
	v_add_f32_e32 v118, v89, v118
	v_add_f32_e32 v118, v90, v118
	v_add_f32_e32 v118, v91, v118
	v_cvt_pk_bf16_f32 v152, v86, v87
	v_cvt_pk_bf16_f32 v153, v88, v89
	ds_read_b64_tr_b16 v[86:87], v220 offset:44032
	ds_read_b64_tr_b16 v[88:89], v220 offset:44544
	v_add_f32_e32 v118, v92, v118
	v_add_f32_e32 v118, v93, v118
	v_add_f32_e32 v118, v94, v118
	v_add_f32_e32 v118, v95, v118
	v_cvt_pk_bf16_f32 v146, v90, v91
	v_cvt_pk_bf16_f32 v147, v92, v93
	s_waitcnt lgkmcnt(14)
	v_mfma_f32_32x32x16_bf16 v[98:113], v[134:137], v[154:157], v[98:113]
	ds_read_b64_tr_b16 v[90:91], v220 offset:48128
	ds_read_b64_tr_b16 v[92:93], v220 offset:48640
	v_mfma_f32_32x32x16_bf16 v[66:81], v[130:133], v[154:157], v[66:81]
	v_add_f32_e32 v118, v96, v118
	v_add_f32_e32 v118, v97, v118
	v_add_f32_e32 v118, 0, v118
	v_cvt_pk_bf16_f32 v148, v94, v95
	v_cvt_pk_bf16_f32 v149, v96, v97
	v_lshl_add_u64 v[94:95], v[210:211], 0, s[52:53]
	s_mov_b32 s4, m0
	s_mov_b32 m0, s5
	s_nop 0
	global_load_lds_dwordx4 v[94:95], off
	s_mov_b32 m0, s4
	v_add_f32_e32 v118, v190, v118
	s_waitcnt lgkmcnt(14)
	v_mfma_f32_32x32x16_bf16 v[18:33], v[166:169], v[212:215], v[18:33]
	v_exp_f32_e32 v98, v98
	v_exp_f32_e32 v99, v99
	v_exp_f32_e32 v100, v100
	v_exp_f32_e32 v101, v101
	s_waitcnt lgkmcnt(12)
	v_mfma_f32_32x32x16_bf16 v[34:49], v[166:169], v[114:117], v[34:49]
	v_exp_f32_e32 v102, v102
	v_exp_f32_e32 v103, v103
	v_exp_f32_e32 v104, v104
	v_exp_f32_e32 v105, v105
	ds_read_b128 v[128:131], v219 offset:8192
	ds_read_b128 v[132:135], v219 offset:8704
	s_waitcnt lgkmcnt(12)
	v_mfma_f32_32x32x16_bf16 v[18:33], v[158:161], v[138:141], v[18:33]
	v_exp_f32_e32 v106, v106
	v_exp_f32_e32 v107, v107
	v_exp_f32_e32 v108, v108
	v_exp_f32_e32 v109, v109
	ds_read_b128 v[136:139], v219 offset:10240
	ds_read_b128 v[140:143], v219 offset:10752
	s_waitcnt lgkmcnt(12)
	v_mfma_f32_32x32x16_bf16 v[34:49], v[158:161], v[120:123], v[34:49]
	v_exp_f32_e32 v110, v110
	v_exp_f32_e32 v111, v111
	v_exp_f32_e32 v112, v112
	v_exp_f32_e32 v113, v113
	ds_read_b128 v[120:123], v219 offset:12288
	ds_read_b128 v[178:181], v219 offset:12800
	s_waitcnt lgkmcnt(12)
	v_mfma_f32_32x32x16_bf16 v[18:33], v[150:153], v[124:127], v[18:33]
	v_exp_f32_e32 v66, v66
	v_exp_f32_e32 v67, v67
	v_exp_f32_e32 v68, v68
	v_exp_f32_e32 v69, v69
	ds_read_b128 v[124:127], v219 offset:14336
	ds_read_b128 v[114:117], v219 offset:14848
	s_waitcnt lgkmcnt(12)
	v_mfma_f32_32x32x16_bf16 v[34:49], v[150:153], v[82:85], v[34:49]
	v_exp_f32_e32 v70, v70
	v_exp_f32_e32 v71, v71
	v_exp_f32_e32 v72, v72
	v_exp_f32_e32 v73, v73
	s_waitcnt lgkmcnt(10)
	v_mfma_f32_32x32x16_bf16 v[18:33], v[146:149], v[86:89], v[18:33]
	v_exp_f32_e32 v74, v74
	v_exp_f32_e32 v75, v75
	v_exp_f32_e32 v76, v76
	v_exp_f32_e32 v77, v77
	s_waitcnt lgkmcnt(8)
	v_mfma_f32_32x32x16_bf16 v[34:49], v[146:149], v[90:93], v[34:49]
	v_exp_f32_e32 v78, v78
	v_exp_f32_e32 v79, v79
	v_exp_f32_e32 v80, v80
	v_exp_f32_e32 v81, v81
	s_waitcnt vmcnt(0) lgkmcnt(0)
	s_barrier
; #define WAIT_BAR(N) asm volatile("s_waitcnt vmcnt(" #N ") lgkmcnt(0)\n\ts_barrier":::"memory")
;   #define RESC() do{}while(0)
;   #define ROT() do{sl_prev=sl_cur;sl_cur=sl_next;sl_next=(sl_next==(NSLOT-1)*SLOTB)?0:sl_next+SLOTB;}while(0)
;   #define ENDW(tt) do{ if((tt)+3<NT){WAIT_BAR(2);} else if((tt)+2<NT){WAIT_BAR(1);} else {WAIT_BAR(0);} }while(0)
; template<int THRL> __device__ __forceinline__ void attn_unit(int b,int h,int qb,const bf16*Q,const bf16*__restrict__ K,const bf16*__restrict__ V,bf16*O,char*shm,float m2){
;     ...
;   int t=1;
;   for(;t+5<NT;t+=2){
;     STEP(pB0,pB1,pA0,pA1,t,true,true,true);     WAIT_BAR(2); RESC(); ROT();
;     STEP(pA0,pA1,pB0,pB1,t+1,true,true,true);   WAIT_BAR(2); RESC(); ROT();
;   }
;     ...
;   for(;t+1<NT;t+=2){
;     STEP(pB0,pB1,pA0,pA1,t,(t+3<NT),(t+1<NT),(t+1<NT));       ENDW(t);   RESC(); ROT();
;     STEP(pA0,pA1,pB0,pB1,t+1,(t+4<NT),(t+2<NT),(t+2<NT));     ENDW(t+1); RESC(); ROT();
;   }
;   STEP(pB0,pB1,pA0,pA1,NT-1,false,false,false); RESC();
	ds_read_b64_tr_b16 v[182:183], v220 offset:24576
	ds_read_b64_tr_b16 v[184:185], v220 offset:25088
	v_add_f32_e32 v82, v98, v99
	v_add_f32_e32 v82, v100, v82
	v_add_f32_e32 v82, v101, v82
	v_add_f32_e32 v82, v102, v82
	v_add_f32_e32 v119, v103, v82
	v_cvt_pk_bf16_f32 v166, v98, v99
	v_cvt_pk_bf16_f32 v167, v100, v101
	s_waitcnt lgkmcnt(9)
	v_mfma_f32_32x32x16_bf16 v[82:97], v[128:131], v[174:177], v[50:65]
	ds_read_b64_tr_b16 v[98:99], v220 offset:28672
	ds_read_b64_tr_b16 v[100:101], v220 offset:29184
	s_waitcnt lgkmcnt(10)
	v_mfma_f32_32x32x16_bf16 v[50:65], v[132:135], v[174:177], v[50:65]
	v_add_f32_e32 v119, v104, v119
	v_add_f32_e32 v119, v105, v119
	v_add_f32_e32 v119, v106, v119
	v_add_f32_e32 v119, v107, v119
	v_cvt_pk_bf16_f32 v168, v102, v103
	v_cvt_pk_bf16_f32 v169, v104, v105
	ds_read_b64_tr_b16 v[102:103], v220 offset:25600
	ds_read_b64_tr_b16 v[104:105], v220 offset:26112
	v_add_f32_e32 v119, v108, v119
	v_add_f32_e32 v119, v109, v119
	v_add_f32_e32 v119, v110, v119
	v_add_f32_e32 v119, v111, v119
	v_cvt_pk_bf16_f32 v158, v106, v107
	v_cvt_pk_bf16_f32 v159, v108, v109
	s_waitcnt lgkmcnt(11)
	v_mfma_f32_32x32x16_bf16 v[82:97], v[136:139], v[170:173], v[82:97]
	ds_read_b64_tr_b16 v[106:107], v220 offset:29696
	ds_read_b64_tr_b16 v[108:109], v220 offset:30208
	s_waitcnt lgkmcnt(12)
	v_mfma_f32_32x32x16_bf16 v[50:65], v[140:143], v[170:173], v[50:65]
	v_add_f32_e32 v119, v112, v119
	v_add_f32_e32 v119, v113, v119
	v_add_f32_e32 v119, v66, v119
	v_add_f32_e32 v119, v67, v119
	v_cvt_pk_bf16_f32 v160, v110, v111
	v_cvt_pk_bf16_f32 v161, v112, v113
	ds_read_b64_tr_b16 v[110:111], v220 offset:26624
	ds_read_b64_tr_b16 v[112:113], v220 offset:27136
	v_add_f32_e32 v119, v68, v119
	v_add_f32_e32 v119, v69, v119
	v_add_f32_e32 v119, v70, v119
	v_add_f32_e32 v119, v71, v119
	v_cvt_pk_bf16_f32 v150, v66, v67
	v_cvt_pk_bf16_f32 v151, v68, v69
	s_waitcnt lgkmcnt(13)
	v_mfma_f32_32x32x16_bf16 v[82:97], v[120:123], v[162:165], v[82:97]
	ds_read_b64_tr_b16 v[66:67], v220 offset:30720
	ds_read_b64_tr_b16 v[68:69], v220 offset:31232
	s_waitcnt lgkmcnt(14)
	v_mfma_f32_32x32x16_bf16 v[50:65], v[178:181], v[162:165], v[50:65]
	v_add_f32_e32 v119, v72, v119
	v_add_f32_e32 v119, v73, v119
	v_add_f32_e32 v119, v74, v119
	v_add_f32_e32 v119, v75, v119
	v_cvt_pk_bf16_f32 v152, v70, v71
	v_cvt_pk_bf16_f32 v153, v72, v73
	ds_read_b64_tr_b16 v[70:71], v220 offset:27648
	ds_read_b64_tr_b16 v[72:73], v220 offset:28160
	v_add_f32_e32 v119, v76, v119
	v_add_f32_e32 v119, v77, v119
	v_add_f32_e32 v119, v78, v119
	v_add_f32_e32 v119, v79, v119
	v_cvt_pk_bf16_f32 v146, v74, v75
	v_cvt_pk_bf16_f32 v147, v76, v77
	s_waitcnt lgkmcnt(14)
	v_mfma_f32_32x32x16_bf16 v[82:97], v[124:127], v[154:157], v[82:97]
	ds_read_b64_tr_b16 v[74:75], v220 offset:31744
	ds_read_b64_tr_b16 v[76:77], v220 offset:32256
	v_mfma_f32_32x32x16_bf16 v[50:65], v[114:117], v[154:157], v[50:65]
	v_add_f32_e32 v114, v80, v119
	v_add_f32_e32 v114, v81, v114
	v_add_f32_e32 v114, 0, v114
	v_cvt_pk_bf16_f32 v148, v78, v79
	v_cvt_pk_bf16_f32 v149, v80, v81
	s_waitcnt lgkmcnt(14)
	v_mfma_f32_32x32x16_bf16 v[18:33], v[166:169], v[182:185], v[18:33]
	s_nop 1
	v_exp_f32_e32 v82, v82
	v_exp_f32_e32 v83, v83
	v_exp_f32_e32 v84, v84
	v_exp_f32_e32 v85, v85
	s_waitcnt lgkmcnt(12)
	v_mfma_f32_32x32x16_bf16 v[34:49], v[166:169], v[98:101], v[34:49]
	v_exp_f32_e32 v86, v86
	v_exp_f32_e32 v87, v87
	v_exp_f32_e32 v88, v88
	v_exp_f32_e32 v89, v89
	s_waitcnt lgkmcnt(10)
	v_mfma_f32_32x32x16_bf16 v[18:33], v[158:161], v[102:105], v[18:33]
	v_exp_f32_e32 v90, v90
	v_exp_f32_e32 v91, v91
	v_exp_f32_e32 v92, v92
	v_exp_f32_e32 v93, v93
	s_waitcnt lgkmcnt(8)
	v_mfma_f32_32x32x16_bf16 v[34:49], v[158:161], v[106:109], v[34:49]
	v_exp_f32_e32 v94, v94
	v_exp_f32_e32 v95, v95
	v_exp_f32_e32 v96, v96
	v_exp_f32_e32 v97, v97
	s_waitcnt lgkmcnt(6)
; #define SBAR() __builtin_amdgcn_sched_barrier(0)
;   #define PKW(P,B) cvtpk_s(P[B],P[B+1])
; template<int THRL> __device__ __forceinline__ void attn_unit(int b,int h,int qb,const bf16*Q,const bf16*__restrict__ K,const bf16*__restrict__ V,bf16*O,char*shm,float m2){
;     ...
;   { float sacc=pB0[0]+pB0[1]; _Pragma("unroll") for(int r=2;r<16;++r)sacc+=pB0[r]; _Pragma("unroll") for(int r=0;r<16;++r)sacc+=pB1[r]; l_reg+=sacc;
;     pw0=(u32x4){PKW(pB0,0),PKW(pB0,2),PKW(pB0,4),PKW(pB0,6)};pw1=(u32x4){PKW(pB0,8),PKW(pB0,10),PKW(pB0,12),PKW(pB0,14)};pw2=(u32x4){PKW(pB1,0),PKW(pB1,2),PKW(pB1,4),PKW(pB1,6)};pw3=(u32x4){PKW(pB1,8),PKW(pB1,10),PKW(pB1,12),PKW(pB1,14)};
;     SBAR(); pv(o,vb0+sl_cur,PAF(0),PAF(1),PAF(2),PAF(3)); }
;     ...
;   {auto rr=__builtin_amdgcn_permlane32_swap(__float_as_uint(l_reg),__float_as_uint(l_reg),false,false);l_reg=__uint_as_float(rr[0])+__uint_as_float(rr[1]);}
;   if(hi==0)wsf[32+r32]=l_reg;asm volatile("s_waitcnt lgkmcnt(0)":::"memory");
	v_mfma_f32_32x32x16_bf16 v[18:33], v[150:153], v[110:113], v[18:33]
	v_exp_f32_e32 v50, v50
	v_exp_f32_e32 v51, v51
	v_exp_f32_e32 v52, v52
	v_exp_f32_e32 v53, v53
	s_waitcnt lgkmcnt(4)
	v_mfma_f32_32x32x16_bf16 v[34:49], v[150:153], v[66:69], v[34:49]
	v_exp_f32_e32 v54, v54
	v_exp_f32_e32 v55, v55
	v_exp_f32_e32 v56, v56
	v_exp_f32_e32 v57, v57
	s_waitcnt lgkmcnt(2)
	v_mfma_f32_32x32x16_bf16 v[18:33], v[146:149], v[70:73], v[18:33]
	v_exp_f32_e32 v58, v58
	v_exp_f32_e32 v59, v59
	v_exp_f32_e32 v60, v60
	v_exp_f32_e32 v61, v61
	s_waitcnt lgkmcnt(0)
	v_mfma_f32_32x32x16_bf16 v[34:49], v[146:149], v[74:77], v[34:49]
	v_exp_f32_e32 v62, v62
	v_exp_f32_e32 v63, v63
	v_exp_f32_e32 v64, v64
	v_exp_f32_e32 v65, v65
	v_add_f32_e32 v66, v82, v83
	v_add_f32_e32 v66, v84, v66
	v_add_f32_e32 v66, v85, v66
	v_add_f32_e32 v66, v86, v66
	v_add_f32_e32 v66, v87, v66
	v_add_f32_e32 v66, v88, v66
	v_add_f32_e32 v66, v89, v66
	v_add_f32_e32 v66, v90, v66
	v_add_f32_e32 v66, v91, v66
	v_add_f32_e32 v66, v92, v66
	v_add_f32_e32 v66, v93, v66
	v_add_f32_e32 v66, v94, v66
	v_add_f32_e32 v66, v95, v66
	v_add_f32_e32 v66, v96, v66
	v_add_f32_e32 v66, v97, v66
	v_add_f32_e32 v66, v50, v66
	v_add_f32_e32 v66, v51, v66
	v_add_f32_e32 v66, v52, v66
	v_add_f32_e32 v66, v53, v66
	v_add_f32_e32 v66, v54, v66
	v_add_f32_e32 v66, v55, v66
	v_add_f32_e32 v66, v56, v66
	v_add_f32_e32 v66, v57, v66
	v_add_f32_e32 v66, v58, v66
	v_add_f32_e32 v66, v59, v66
	v_add_f32_e32 v66, v60, v66
	v_add_f32_e32 v66, v61, v66
	v_add_f32_e32 v66, v62, v66
	v_add_f32_e32 v66, v63, v66
	v_add_f32_e32 v66, v64, v66
	v_add_f32_e32 v66, v65, v66
	v_add_f32_e32 v67, v118, v114
	v_add_f32_e32 v66, v67, v66
	v_cvt_pk_bf16_f32 v50, v50, v51
	v_cvt_pk_bf16_f32 v68, v82, v83
	v_cvt_pk_bf16_f32 v69, v84, v85
	v_cvt_pk_bf16_f32 v70, v86, v87
	v_cvt_pk_bf16_f32 v71, v88, v89
	v_cvt_pk_bf16_f32 v72, v90, v91
	v_cvt_pk_bf16_f32 v73, v92, v93
	v_cvt_pk_bf16_f32 v74, v94, v95
	v_cvt_pk_bf16_f32 v75, v96, v97
	v_cvt_pk_bf16_f32 v51, v52, v53
	v_cvt_pk_bf16_f32 v52, v54, v55
	v_cvt_pk_bf16_f32 v53, v56, v57
	v_cvt_pk_bf16_f32 v54, v58, v59
	v_cvt_pk_bf16_f32 v55, v60, v61
	v_cvt_pk_bf16_f32 v56, v62, v63
	v_cvt_pk_bf16_f32 v57, v64, v65
	ds_read_b64_tr_b16 v[58:59],v221 offset:0
	ds_read_b64_tr_b16 v[60:61],v221 offset:512
	ds_read_b64_tr_b16 v[62:63],v221 offset:1024
	ds_read_b64_tr_b16 v[64:65],v221 offset:1536
	ds_read_b64_tr_b16 v[76:77],v221 offset:2048
	ds_read_b64_tr_b16 v[78:79],v221 offset:2560
	ds_read_b64_tr_b16 v[80:81],v221 offset:3072
	ds_read_b64_tr_b16 v[82:83],v221 offset:3584
	s_waitcnt lgkmcnt(0)
	s_nop 0
	v_mfma_f32_32x32x16_bf16 v[18:33], v[68:71], v[58:61], v[18:33]
	ds_read_b64_tr_b16 v[58:59],v221 offset:4096
	ds_read_b64_tr_b16 v[60:61],v221 offset:4608
	v_mfma_f32_32x32x16_bf16 v[18:33], v[72:75], v[62:65], v[18:33]
	ds_read_b64_tr_b16 v[62:63],v221 offset:5120
	ds_read_b64_tr_b16 v[64:65],v221 offset:5632
	v_mfma_f32_32x32x16_bf16 v[18:33], v[50:53], v[76:79], v[18:33]
	ds_read_b64_tr_b16 v[76:77],v221 offset:6144
	ds_read_b64_tr_b16 v[78:79],v221 offset:6656
	v_mfma_f32_32x32x16_bf16 v[18:33], v[54:57], v[80:83], v[18:33]
	ds_read_b64_tr_b16 v[80:81],v221 offset:7168
	ds_read_b64_tr_b16 v[82:83],v221 offset:7680
	s_waitcnt lgkmcnt(0)
	v_mfma_f32_32x32x16_bf16 v[34:49], v[68:71], v[58:61], v[34:49]
	v_mfma_f32_32x32x16_bf16 v[34:49], v[72:75], v[62:65], v[34:49]
	v_mfma_f32_32x32x16_bf16 v[34:49], v[50:53], v[76:79], v[34:49]
	v_mov_b32_e32 v50, v66
	s_nop 1
	v_permlane32_swap_b32_e32 v66, v50
	v_mfma_f32_32x32x16_bf16 v[34:49], v[54:57], v[80:83], v[34:49]
	s_and_saveexec_b64 s[4:5], s[2:3]
	s_cbranch_execz .LBB0_823
	v_add_f32_e32 v50, v66, v50
	v_lshl_add_u32 v51, v1, 2, s0
	ds_write_b32 v51, v50 offset:49280
	s_branch .LBB0_823
